# GEMM / mini-GEMM accumulator zero-init: 128 (32) v_mov_b32 replaced by 64 (16) v_mov_b64 per tile (on top of v36)
# speedup vs baseline: 1.0031x; 1.0031x over previous
; template <class Epi, class Sched, bool ALIGN_EPI = false, bool SP2 = false>
; __device__ __forceinline__ void gemm_phase(PG8_LAS unsigned char* lds, const Gemm g, const Sched& S, const Epi& E, const int tid) {
;     ...
;         const bool has_next = S.next(ui + 1, nxt);
;         const char* nA = has_next ? (const char*)g.A + (size_t)nxt.pm * tstep : cA; const char* nB = has_next ? (const char*)g.Bt + (size_t)nxt.pn * tstep : cB;
;     ...
; #pragma unroll
;         for (int a = 0; a < 2; ++a)
; #pragma unroll
;             for (int b = 0; b < 2; ++b)
; #pragma unroll
;                 for (int m = 0; m < 4; ++m)
; #pragma unroll
;                     for (int n = 0; n < 2; ++n) acc[a][b][m][n] = (f32x4){0.f, 0.f, 0.f, 0.f};
;         cur = nxt; cA = nA; cB = nB; ++ui;
.LBB0_59:
	v_mov_b64_e32 v[2:3], 0x1000
	s_ashr_i32 s9, s8, 31
	v_cmp_lt_i64_e32 vcc, s[10:11], v[2:3]
	s_lshl_b64 s[10:11], s[8:9], 20
	v_readlane_b32 s12, v253, 24
	v_readlane_b32 s13, v253, 25
	s_add_u32 s10, s12, s10
	s_addc_u32 s11, s13, s11
	s_and_b64 s[12:13], vcc, exec
	s_cselect_b32 s9, s11, s15
	s_cselect_b32 s38, s10, s14
	s_ashr_i32 s7, s6, 31
	s_lshl_b64 s[12:13], s[6:7], 20
	s_add_u32 s12, s22, s12
	s_addc_u32 s13, s23, s13
	s_and_b64 s[18:19], vcc, exec
	s_cselect_b32 s7, s13, s17
	s_cselect_b32 s39, s12, s16
	s_add_u32 s14, s14, 0x80080
	s_addc_u32 s15, s15, 0
	s_add_u32 s40, s16, 0x100
	v_mov_b64_e32 v[2:3], 0
	v_mov_b64_e32 v[4:5], 0
	v_mov_b64_e32 v[6:7], 0
	v_mov_b64_e32 v[8:9], 0
	v_mov_b64_e32 v[10:11], 0
	v_mov_b64_e32 v[12:13], 0
	v_mov_b64_e32 v[14:15], 0
	v_mov_b64_e32 v[16:17], 0
	v_mov_b64_e32 v[18:19], 0
	v_mov_b64_e32 v[20:21], 0
	v_mov_b64_e32 v[22:23], 0
	v_mov_b64_e32 v[24:25], 0
	v_mov_b64_e32 v[26:27], 0
	v_mov_b64_e32 v[28:29], 0
	v_mov_b64_e32 v[30:31], 0
	v_mov_b64_e32 v[32:33], 0
	v_mov_b64_e32 v[34:35], 0
	v_mov_b64_e32 v[36:37], 0
	v_mov_b64_e32 v[38:39], 0
	v_mov_b64_e32 v[40:41], 0
	v_mov_b64_e32 v[42:43], 0
	v_mov_b64_e32 v[44:45], 0
	v_mov_b64_e32 v[46:47], 0
	v_mov_b64_e32 v[48:49], 0
	v_mov_b64_e32 v[50:51], 0
	v_mov_b64_e32 v[52:53], 0
	v_mov_b64_e32 v[54:55], 0
	v_mov_b64_e32 v[56:57], 0
	v_mov_b64_e32 v[58:59], 0
	v_mov_b64_e32 v[60:61], 0
	v_mov_b64_e32 v[62:63], 0
	v_mov_b64_e32 v[64:65], 0
	v_mov_b64_e32 v[66:67], 0
	v_mov_b64_e32 v[68:69], 0
	v_mov_b64_e32 v[70:71], 0
	v_mov_b64_e32 v[72:73], 0
	v_mov_b64_e32 v[74:75], 0
	v_mov_b64_e32 v[76:77], 0
	v_mov_b64_e32 v[78:79], 0
	v_mov_b64_e32 v[80:81], 0
	v_mov_b64_e32 v[82:83], 0
	v_mov_b64_e32 v[84:85], 0
	v_mov_b64_e32 v[86:87], 0
	v_mov_b64_e32 v[88:89], 0
	v_mov_b64_e32 v[90:91], 0
	v_mov_b64_e32 v[92:93], 0
	v_mov_b64_e32 v[94:95], 0
	v_mov_b64_e32 v[96:97], 0
	v_mov_b64_e32 v[98:99], 0
	v_mov_b64_e32 v[100:101], 0
	v_mov_b64_e32 v[102:103], 0
	v_mov_b64_e32 v[104:105], 0
	v_mov_b64_e32 v[106:107], 0
	v_mov_b64_e32 v[108:109], 0
	v_mov_b64_e32 v[110:111], 0
	v_mov_b64_e32 v[112:113], 0
	v_mov_b64_e32 v[114:115], 0
	v_mov_b64_e32 v[116:117], 0
	v_mov_b64_e32 v[118:119], 0
	v_mov_b64_e32 v[120:121], 0
	v_mov_b64_e32 v[122:123], 0
	v_mov_b64_e32 v[124:125], 0
	v_mov_b64_e32 v[126:127], 0
	v_mov_b64_e32 v[128:129], 0
	s_addc_u32 s41, s17, 0
	s_mov_b32 s42, -2

; __device__ __forceinline__ void mini_gemm(PG8_LAS unsigned char* lds, const bf16_t* A, const bf16_t* Bt, bf16_t* O, int ldc, int N, int blk, int G, const int tid) {
;     ...
;     for (int u = blk; u < nunits; u += G) {
;         const int tm = u & 3, tn = u >> 2;
;         const char* cA = (const char*)(A + (size_t)tm * 128 * K); const char* cB = (const char*)(Bt + (size_t)tn * 128 * K);
;         f32x4 acc[4][2];
; #pragma unroll
;         for (int m = 0; m < 4; ++m)
; #pragma unroll
;             for (int n = 0; n < 2; ++n) acc[m][n] = (f32x4){0.f, 0.f, 0.f, 0.f};
;         MG_STAGE(0, 0); MG_STAGE(1, 1); MG_STAGE(2, 2);
.LBB0_67:
	s_and_b32 s2, s21, 3
	s_lshl_b32 s28, s2, 19
	s_ashr_i32 s2, s7, 2
	s_and_b32 s8, s7, 3
	s_ashr_i32 s3, s2, 31
	s_lshl_b64 s[4:5], s[2:3], 19
	s_lshl_b32 s3, s8, 19
	s_add_u32 s10, s58, s3
	s_addc_u32 s11, s59, 0
	s_add_u32 s12, s22, s4
	s_addc_u32 s13, s23, s5
	v_lshl_add_u64 v[2:3], s[10:11], 0, v[130:131]
	s_mov_b32 m0, s6
	v_lshl_add_u64 v[4:5], s[12:13], 0, v[0:1]
	global_load_lds_dwordx4 v[2:3], off
	s_add_i32 m0, s6, 0x4000
	v_lshl_add_u64 v[6:7], s[10:11], 0, v[132:133]
	global_load_lds_dwordx4 v[4:5], off
	s_add_i32 m0, s6, 0x2000
	v_lshl_add_u64 v[8:9], s[12:13], 0, v[134:135]
	global_load_lds_dwordx4 v[6:7], off
	s_add_i32 m0, s6, 0x6000
	v_lshl_add_u64 v[10:11], v[2:3], 0, s[0:1]
	global_load_lds_dwordx4 v[8:9], off
	s_add_i32 m0, s6, 0x8000
	s_mov_b64 s[10:11], 0x100
	global_load_lds_dwordx4 v[10:11], off
	v_lshl_add_u64 v[10:11], v[4:5], 0, s[0:1]
	s_add_i32 m0, s6, 0xc000
	v_lshl_add_u64 v[2:3], v[2:3], 0, s[10:11]
	global_load_lds_dwordx4 v[10:11], off
	v_lshl_add_u64 v[10:11], v[6:7], 0, s[0:1]
	s_add_i32 m0, s6, 0xa000
	v_lshl_add_u64 v[42:43], v[34:35], 0, s[28:29]
	global_load_lds_dwordx4 v[10:11], off
	v_lshl_add_u64 v[10:11], v[8:9], 0, s[0:1]
	s_add_i32 m0, s6, 0xe000
	v_lshl_add_u64 v[44:45], v[36:37], 0, s[28:29]
	global_load_lds_dwordx4 v[10:11], off
	s_add_i32 m0, s6, 0x10000
	v_lshl_add_u64 v[46:47], v[38:39], 0, s[4:5]
	global_load_lds_dwordx4 v[2:3], off
	v_lshl_add_u64 v[2:3], v[4:5], 0, s[10:11]
	s_add_i32 m0, s6, 0x14000
	v_lshl_add_u64 v[48:49], v[40:41], 0, s[4:5]
	global_load_lds_dwordx4 v[2:3], off
	v_lshl_add_u64 v[2:3], v[6:7], 0, s[10:11]
	s_add_i32 m0, s6, 0x12000
	s_mov_b64 s[4:5], 0
	global_load_lds_dwordx4 v[2:3], off
	v_lshl_add_u64 v[2:3], v[8:9], 0, s[10:11]
	s_add_i32 m0, s6, 0x16000
	s_mov_b32 s3, 0
	global_load_lds_dwordx4 v[2:3], off
	v_mov_b64_e32 v[2:3], 0
	v_mov_b64_e32 v[4:5], 0
	v_mov_b64_e32 v[6:7], 0
	v_mov_b64_e32 v[8:9], 0
	v_mov_b64_e32 v[10:11], 0
	v_mov_b64_e32 v[12:13], 0
	v_mov_b64_e32 v[14:15], 0
	v_mov_b64_e32 v[16:17], 0
	v_mov_b64_e32 v[18:19], 0
	v_mov_b64_e32 v[20:21], 0
	v_mov_b64_e32 v[22:23], 0
	v_mov_b64_e32 v[24:25], 0
	v_mov_b64_e32 v[26:27], 0
	v_mov_b64_e32 v[28:29], 0
	v_mov_b64_e32 v[30:31], 0
	v_mov_b64_e32 v[32:33], 0

; template <class Epi, class Sched, bool ALIGN_EPI = false, bool SP2 = false>
; __device__ __forceinline__ void gemm_phase(PG8_LAS unsigned char* lds, const Gemm g, const Sched& S, const Epi& E, const int tid) {
;     ...
;         const bool has_next = S.next(ui + 1, nxt);
;         const char* nA = has_next ? (const char*)g.A + (size_t)nxt.pm * tstep : cA; const char* nB = has_next ? (const char*)g.Bt + (size_t)nxt.pn * tstep : cB;
;     ...
; #pragma unroll
;         for (int a = 0; a < 2; ++a)
; #pragma unroll
;             for (int b = 0; b < 2; ++b)
; #pragma unroll
;                 for (int m = 0; m < 4; ++m)
; #pragma unroll
;                     for (int n = 0; n < 2; ++n) acc[a][b][m][n] = (f32x4){0.f, 0.f, 0.f, 0.f};
;         cur = nxt; cA = nA; cB = nB; ++ui;
.LBB0_495:
	s_ashr_i32 s9, s8, 31
	v_cmp_lt_i64_e32 vcc, s[10:11], v[156:157]
	s_lshl_b64 s[10:11], s[8:9], 20
	s_add_u32 s10, s56, s10
	s_addc_u32 s11, s57, s11
	s_and_b64 s[12:13], vcc, exec
	s_cselect_b32 s9, s11, s15
	s_cselect_b32 s38, s10, s14
	s_ashr_i32 s7, s6, 31
	s_lshl_b64 s[12:13], s[6:7], 20
	s_add_u32 s12, s22, s12
	s_addc_u32 s13, s23, s13
	s_and_b64 s[18:19], vcc, exec
	s_cselect_b32 s7, s13, s17
	s_cselect_b32 s39, s12, s16
	s_add_u32 s14, s14, 0x80080
	s_addc_u32 s15, s15, 0
	s_add_u32 s40, s16, 0x100
	v_mov_b64_e32 v[2:3], 0
	v_mov_b64_e32 v[4:5], 0
	v_mov_b64_e32 v[6:7], 0
	v_mov_b64_e32 v[8:9], 0
	v_mov_b64_e32 v[10:11], 0
	v_mov_b64_e32 v[12:13], 0
	v_mov_b64_e32 v[14:15], 0
	v_mov_b64_e32 v[16:17], 0
	v_mov_b64_e32 v[18:19], 0
	v_mov_b64_e32 v[20:21], 0
	v_mov_b64_e32 v[22:23], 0
	v_mov_b64_e32 v[24:25], 0
	v_mov_b64_e32 v[26:27], 0
	v_mov_b64_e32 v[28:29], 0
	v_mov_b64_e32 v[30:31], 0
	v_mov_b64_e32 v[32:33], 0
	v_mov_b64_e32 v[34:35], 0
	v_mov_b64_e32 v[36:37], 0
	v_mov_b64_e32 v[38:39], 0
	v_mov_b64_e32 v[40:41], 0
	v_mov_b64_e32 v[42:43], 0
	v_mov_b64_e32 v[44:45], 0
	v_mov_b64_e32 v[46:47], 0
	v_mov_b64_e32 v[48:49], 0
	v_mov_b64_e32 v[50:51], 0
	v_mov_b64_e32 v[52:53], 0
	v_mov_b64_e32 v[54:55], 0
	v_mov_b64_e32 v[56:57], 0
	v_mov_b64_e32 v[58:59], 0
	v_mov_b64_e32 v[60:61], 0
	v_mov_b64_e32 v[62:63], 0
	v_mov_b64_e32 v[64:65], 0
	v_mov_b64_e32 v[66:67], 0
	v_mov_b64_e32 v[68:69], 0
	v_mov_b64_e32 v[70:71], 0
	v_mov_b64_e32 v[72:73], 0
	v_mov_b64_e32 v[74:75], 0
	v_mov_b64_e32 v[76:77], 0
	v_mov_b64_e32 v[78:79], 0
	v_mov_b64_e32 v[80:81], 0
	v_mov_b64_e32 v[82:83], 0
	v_mov_b64_e32 v[84:85], 0
	v_mov_b64_e32 v[86:87], 0
	v_mov_b64_e32 v[88:89], 0
	v_mov_b64_e32 v[90:91], 0
	v_mov_b64_e32 v[92:93], 0
	v_mov_b64_e32 v[94:95], 0
	v_mov_b64_e32 v[96:97], 0
	v_mov_b64_e32 v[98:99], 0
	v_mov_b64_e32 v[100:101], 0
	v_mov_b64_e32 v[102:103], 0
	v_mov_b64_e32 v[104:105], 0
	v_mov_b64_e32 v[106:107], 0
	v_mov_b64_e32 v[108:109], 0
	v_mov_b64_e32 v[110:111], 0
	v_mov_b64_e32 v[112:113], 0
	v_mov_b64_e32 v[114:115], 0
	v_mov_b64_e32 v[116:117], 0
	v_mov_b64_e32 v[118:119], 0
	v_mov_b64_e32 v[120:121], 0
	v_mov_b64_e32 v[122:123], 0
	v_mov_b64_e32 v[124:125], 0
	v_mov_b64_e32 v[126:127], 0
	v_mov_b64_e32 v[128:129], 0
	s_addc_u32 s41, s17, 0
	s_mov_b32 s42, -2

; __device__ __forceinline__ void mini_gemm(PG8_LAS unsigned char* lds, const bf16_t* A, const bf16_t* Bt, bf16_t* O, int ldc, int N, int blk, int G, const int tid) {
;     ...
;     for (int u = blk; u < nunits; u += G) {
;         const int tm = u & 3, tn = u >> 2;
;         const char* cA = (const char*)(A + (size_t)tm * 128 * K); const char* cB = (const char*)(Bt + (size_t)tn * 128 * K);
;         f32x4 acc[4][2];
; #pragma unroll
;         for (int m = 0; m < 4; ++m)
; #pragma unroll
;             for (int n = 0; n < 2; ++n) acc[m][n] = (f32x4){0.f, 0.f, 0.f, 0.f};
;         MG_STAGE(0, 0); MG_STAGE(1, 1); MG_STAGE(2, 2);
.LBB0_503:
	s_and_b32 s2, s21, 3
	s_lshl_b32 s28, s2, 19
	s_ashr_i32 s2, s7, 2
	s_and_b32 s8, s7, 3
	s_ashr_i32 s3, s2, 31
	s_lshl_b64 s[4:5], s[2:3], 19
	s_lshl_b32 s3, s8, 19
	v_readlane_b32 s9, v254, 51
	s_add_u32 s10, s9, s3
	v_readlane_b32 s3, v254, 52
	s_addc_u32 s11, s3, 0
	s_add_u32 s12, s22, s4
	s_addc_u32 s13, s23, s5
	v_lshl_add_u64 v[2:3], s[10:11], 0, v[130:131]
	s_mov_b32 m0, s6
	v_lshl_add_u64 v[4:5], s[12:13], 0, v[0:1]
	global_load_lds_dwordx4 v[2:3], off
	s_add_i32 m0, s6, 0x4000
	v_lshl_add_u64 v[6:7], s[10:11], 0, v[132:133]
	global_load_lds_dwordx4 v[4:5], off
	s_add_i32 m0, s6, 0x2000
	v_lshl_add_u64 v[8:9], s[12:13], 0, v[134:135]
	global_load_lds_dwordx4 v[6:7], off
	s_add_i32 m0, s6, 0x6000
	v_lshl_add_u64 v[10:11], v[2:3], 0, s[0:1]
	global_load_lds_dwordx4 v[8:9], off
	s_add_i32 m0, s6, 0x8000
	s_mov_b64 s[10:11], 0x100
	global_load_lds_dwordx4 v[10:11], off
	v_lshl_add_u64 v[10:11], v[4:5], 0, s[0:1]
	s_add_i32 m0, s6, 0xc000
	v_lshl_add_u64 v[2:3], v[2:3], 0, s[10:11]
	global_load_lds_dwordx4 v[10:11], off
	v_lshl_add_u64 v[10:11], v[6:7], 0, s[0:1]
	s_add_i32 m0, s6, 0xa000
	v_lshl_add_u64 v[42:43], v[34:35], 0, s[28:29]
	global_load_lds_dwordx4 v[10:11], off
	v_lshl_add_u64 v[10:11], v[8:9], 0, s[0:1]
	s_add_i32 m0, s6, 0xe000
	v_lshl_add_u64 v[44:45], v[36:37], 0, s[28:29]
	global_load_lds_dwordx4 v[10:11], off
	s_add_i32 m0, s6, 0x10000
	v_lshl_add_u64 v[46:47], v[38:39], 0, s[4:5]
	global_load_lds_dwordx4 v[2:3], off
	v_lshl_add_u64 v[2:3], v[4:5], 0, s[10:11]
	s_add_i32 m0, s6, 0x14000
	v_lshl_add_u64 v[48:49], v[40:41], 0, s[4:5]
	global_load_lds_dwordx4 v[2:3], off
	v_lshl_add_u64 v[2:3], v[6:7], 0, s[10:11]
	s_add_i32 m0, s6, 0x12000
	s_mov_b64 s[4:5], 0
	global_load_lds_dwordx4 v[2:3], off
	v_lshl_add_u64 v[2:3], v[8:9], 0, s[10:11]
	s_add_i32 m0, s6, 0x16000
	s_mov_b32 s3, 0
	global_load_lds_dwordx4 v[2:3], off
	v_mov_b64_e32 v[2:3], 0
	v_mov_b64_e32 v[4:5], 0
	v_mov_b64_e32 v[6:7], 0
	v_mov_b64_e32 v[8:9], 0
	v_mov_b64_e32 v[10:11], 0
	v_mov_b64_e32 v[12:13], 0
	v_mov_b64_e32 v[14:15], 0
	v_mov_b64_e32 v[16:17], 0
	v_mov_b64_e32 v[18:19], 0
	v_mov_b64_e32 v[20:21], 0
	v_mov_b64_e32 v[22:23], 0
	v_mov_b64_e32 v[24:25], 0
	v_mov_b64_e32 v[26:27], 0
	v_mov_b64_e32 v[28:29], 0
	v_mov_b64_e32 v[30:31], 0
	v_mov_b64_e32 v[32:33], 0
